# v24 + P10 row phase: S5 group-major output staged in wave-private LDS and written as full 128-byte lines once per 4 rows (was four 32-byte partial-line stores per row)
# speedup vs baseline: 1.0025x; 1.0025x over previous
; __device__ __forceinline__ float wave_sum(float v) { return lane63(wave_scan_incl(v)); }
; template <bool XSRC_BF, bool XDST_BF> ...
;     ...
;     const int G = gridDim.x, niter = (NTOK / 8 + G - 1) / G;
;     ...
;     vu4 nxb[4], nho[4]; float nxf[4][8];
;     ...
;     int rown = ROW_OF(0);
;     if (rown >= 0) ROW_LOAD(rown)
;     for (int it = 0; it < niter; ++it) {
;         const int row = rown; if (row < 0) break;
;         const int b = seq_of_row(row);
;         float xv[4][8]; vu4 hraw[4];
; #pragma unroll
;         for (int j = 0; j < 4; ++j) { if (XSRC_BF) unpack8(nxb[j], xv[j]); else {
; #pragma unroll
;                 for (int e = 0; e < 8; ++e) xv[j][e] = nxf[j][e]; }
;             hraw[j] = nho[j]; }
;         rown = it + 1 < niter ? ROW_OF(it + 1) : -1;
;         if (rown >= 0) ROW_LOAD(rown)
;         if (ho) {
;             float hv[4][8]; float ss = 0.f;
; #pragma unroll
;             for (int j = 0; j < 4; ++j) { unpack8(hraw[j], hv[j]);
; #pragma unroll
;                 for (int e = 0; e < 8; ++e) ss += hv[j][e] * hv[j][e]; }
;             ss = wave_sum(ss);
;             const float r1 = rsqrtf(ss * (1.0f / DM) + EPSN);
; #pragma unroll
;             for (int j = 0; j < 4; ++j) { float gt[8]; load8f(mgate + (size_t)b * 12288 + 8 * lane + 512 * j, gt);
.LBB0_1093:
.LBB0_1094:
	s_mul_i32 s7, s11, s3
	s_sub_i32 s7, s9, s7
	s_xor_b32 s6, s10, s8
	s_add_i32 s8, s11, 1
	s_sub_i32 s9, s7, s3
	s_cmp_ge_u32 s7, s3
	s_cselect_b32 s8, s8, s11
	s_cselect_b32 s7, s9, s7
	s_add_i32 s9, s8, 1
	s_cmp_ge_u32 s7, s3
	s_cselect_b32 s3, s9, s8
	s_xor_b32 s3, s3, s6
	s_sub_i32 s31, s3, s6
	s_cmp_lt_i32 s31, 1
	s_cselect_b64 s[6:7], -1, 0
	s_xor_b64 s[4:5], s[4:5], -1
	s_or_b64 s[4:5], s[6:7], s[4:5]
	s_mov_b32 s30, 1
	s_and_b64 vcc, exec, s[4:5]
	s_cbranch_vccnz .LBB0_1101
	v_readlane_b32 s4, v254, 8
	v_mov_b32_e32 v67, 0
	v_readlane_b32 s5, v254, 9
	v_lshlrev_b32_e32 v4, 5, v1
	v_mov_b32_e32 v5, v67
	v_lshl_add_u64 v[68:69], s[4:5], 0, v[66:67]
	v_readlane_b32 s4, v254, 4
	v_readlane_b32 s5, v254, 5
	s_add_u32 s33, s82, 0x58000
	v_lshlrev_b32_e32 v2, 3, v1
	v_lshl_add_u64 v[70:71], s[4:5], 0, v[66:67]
	v_lshl_add_u64 v[4:5], s[82:83], 0, v[4:5]
	s_mov_b64 s[4:5], 0x1a000
	v_and_b32_e32 v66, 16, v66
	v_lshrrev_b32_e32 v1, 1, v1
	s_addc_u32 s34, s83, 0
	v_lshl_add_u64 v[72:73], v[4:5], 0, s[4:5]
	v_lshl_add_u64 v[74:75], s[84:85], 0, v[66:67]
	v_mul_u32_u24_e32 v1, 0x500, v1
	s_mov_b32 s3, 0
	s_mov_b64 s[4:5], 0x1000
	s_movk_i32 s35, 0x1000
	s_mov_b64 s[6:7], 0x1800
	v_mov_b32_e32 v84, 0x358637bd
	s_mov_b32 s36, 0x800000
	v_lshlrev_b32_e32 v66, 2, v2
	s_mov_b64 s[8:9], 0x2000
	s_movk_i32 s37, 0x600
	s_mov_b64 s[10:11], 0x3000
	s_movk_i32 s38, 0x3000
	s_mov_b64 s[12:13], 0x3800
	v_mov_b32_e32 v85, 0x8000
	v_mov_b32_e32 v86, 0xc000
	v_mov_b32_e32 v87, 0x3a000000
	v_and_b32_e32 v234, 63, v0
	v_lshrrev_b32_e32 v235, 6, v0
	v_mul_u32_u24_e32 v214, 0x4800, v235
	v_lshrrev_b32_e32 v236, 1, v234
	v_and_b32_e32 v237, 1, v234
	v_lshlrev_b32_e32 v237, 4, v237
	v_mul_u32_u24_e32 v236, 0x90, v236
	v_add3_u32 v210, v214, v236, v237
	v_lshrrev_b32_e32 v236, 3, v234
	v_and_b32_e32 v237, 7, v234
	v_lshlrev_b32_e32 v237, 4, v237
	v_mul_u32_u24_e32 v216, 0x90, v236
	v_add3_u32 v211, v214, v216, v237
	v_mul_u32_u24_e32 v216, 0x1e0000, v236
	v_lshlrev_b32_e32 v235, 7, v235
	v_add3_u32 v216, v216, v237, v235
	v_mov_b32_e32 v217, 0
	v_lshl_add_u64 v[212:213], s[84:85], 0, v[216:217]
	s_mov_b32 s100, 0xf00000
	s_mov_b32 s101, 0
	s_branch .LBB0_1097
.LBB0_1096:
	v_sub_co_u32_e32 v76, vcc, s2, v85
	s_nop 0
	v_readfirstlane_b32 s17, v76
	s_lshr_b32 s17, s17, 12
	s_add_i32 s17, s17, 4
	s_lshr_b32 s39, s2, 13
	s_and_b64 s[26:27], vcc, exec
	s_cselect_b32 s17, s39, s17
	v_lshlrev_b32_e32 v124, 16, v34
	v_and_b32_e32 v125, 0xffff0000, v34
	v_lshlrev_b32_e32 v126, 16, v35
	v_and_b32_e32 v127, 0xffff0000, v35
	v_mad_u64_u32 v[34:35], s[26:27], s17, v86, v[72:73]
	v_lshlrev_b32_e32 v100, 16, v62
	v_and_b32_e32 v101, 0xffff0000, v62
	v_lshlrev_b32_e32 v102, 16, v63
	v_and_b32_e32 v103, 0xffff0000, v63
	v_lshlrev_b32_e32 v104, 16, v64
	v_and_b32_e32 v105, 0xffff0000, v64
	v_lshlrev_b32_e32 v106, 16, v65
	v_and_b32_e32 v107, 0xffff0000, v65
	v_lshlrev_b32_e32 v108, 16, v58
	v_and_b32_e32 v109, 0xffff0000, v58
	v_lshlrev_b32_e32 v110, 16, v59
	v_and_b32_e32 v111, 0xffff0000, v59
	v_lshlrev_b32_e32 v112, 16, v60
	v_and_b32_e32 v113, 0xffff0000, v60
	v_lshlrev_b32_e32 v114, 16, v61
	v_and_b32_e32 v115, 0xffff0000, v61
	v_lshlrev_b32_e32 v116, 16, v54
	v_and_b32_e32 v117, 0xffff0000, v54
	v_lshlrev_b32_e32 v118, 16, v55
	v_and_b32_e32 v119, 0xffff0000, v55
	v_lshlrev_b32_e32 v120, 16, v56
	v_and_b32_e32 v121, 0xffff0000, v56
	v_lshlrev_b32_e32 v122, 16, v57
	v_and_b32_e32 v123, 0xffff0000, v57
	global_load_dwordx4 v[54:57], v[34:35], off offset:16
	global_load_dwordx4 v[58:61], v[34:35], off
	global_load_dwordx4 v[62:65], v[34:35], off offset:2064
	global_load_dwordx4 v[76:79], v[34:35], off offset:2048
	v_add_co_u32_e32 v92, vcc, s35, v34
	v_lshl_add_u64 v[88:89], v[34:35], 0, s[4:5]
	s_nop 0
	v_addc_co_u32_e32 v93, vcc, 0, v35, vcc
	global_load_dwordx4 v[80:83], v[92:93], off
	s_nop 0
	global_load_dwordx4 v[88:91], v[88:89], off offset:16
	v_lshl_add_u64 v[34:35], v[34:35], 0, s[6:7]
	global_load_dwordx4 v[92:95], v[92:93], off offset:2048
	s_nop 0
	global_load_dwordx4 v[96:99], v[34:35], off offset:16
	v_lshlrev_b32_e32 v176, 16, v38
	v_and_b32_e32 v177, 0xffff0000, v38
	v_lshlrev_b32_e32 v172, 16, v39
	v_and_b32_e32 v173, 0xffff0000, v39
	v_pk_mul_f32 v[38:39], v[176:177], v[176:177]
	v_lshlrev_b32_e32 v128, 16, v36
	v_and_b32_e32 v129, 0xffff0000, v36
	v_pk_mul_f32 v[174:175], v[172:173], v[172:173]
	v_add_f32_e32 v36, v38, v39
	v_lshlrev_b32_e32 v170, 16, v40
	v_and_b32_e32 v171, 0xffff0000, v40
	v_add_f32_e32 v36, v174, v36
	v_lshlrev_b32_e32 v166, 16, v41
	v_and_b32_e32 v167, 0xffff0000, v41
	v_pk_mul_f32 v[40:41], v[170:171], v[170:171]
	v_add_f32_e32 v36, v175, v36
	v_add_f32_e32 v36, v40, v36
	v_pk_mul_f32 v[168:169], v[166:167], v[166:167]
	v_add_f32_e32 v36, v41, v36
	v_lshlrev_b32_e32 v164, 16, v42
	v_and_b32_e32 v165, 0xffff0000, v42
	v_add_f32_e32 v36, v168, v36
	v_lshlrev_b32_e32 v160, 16, v43
	v_and_b32_e32 v161, 0xffff0000, v43
	v_pk_mul_f32 v[42:43], v[164:165], v[164:165]
	v_add_f32_e32 v36, v169, v36
	v_add_f32_e32 v36, v42, v36
	v_pk_mul_f32 v[162:163], v[160:161], v[160:161]
	v_add_f32_e32 v36, v43, v36
	v_lshlrev_b32_e32 v158, 16, v44
	v_and_b32_e32 v159, 0xffff0000, v44
	v_add_f32_e32 v36, v162, v36
	v_lshlrev_b32_e32 v154, 16, v45
	v_and_b32_e32 v155, 0xffff0000, v45
	v_pk_mul_f32 v[44:45], v[158:159], v[158:159]
	v_add_f32_e32 v36, v163, v36
	v_add_f32_e32 v36, v44, v36
	v_pk_mul_f32 v[156:157], v[154:155], v[154:155]
	v_add_f32_e32 v36, v45, v36
	v_lshlrev_b32_e32 v152, 16, v46
	v_and_b32_e32 v153, 0xffff0000, v46
	v_add_f32_e32 v36, v156, v36
	v_lshlrev_b32_e32 v148, 16, v47
	v_and_b32_e32 v149, 0xffff0000, v47
; __device__ __forceinline__ vu4 pack8(const float (&f)[8]) { vu4 w; w.x = pg8::cvt_pk_bf16(f[0], f[1]); w.y = pg8::cvt_pk_bf16(f[2], f[3]); w.z = pg8::cvt_pk_bf16(f[4], f[5]); w.w = pg8::cvt_pk_bf16(f[6], f[7]); return w; }
; __device__ __forceinline__ float wave_sum(float v) { return lane63(wave_scan_incl(v)); }
; template <bool XSRC_BF, bool XDST_BF> ...
;     ...
;             ss = wave_sum(ss);
;             const float r1 = rsqrtf(ss * (1.0f / DM) + EPSN);
; #pragma unroll
;             for (int j = 0; j < 4; ++j) { float gt[8]; load8f(mgate + (size_t)b * 12288 + 8 * lane + 512 * j, gt);
; #pragma unroll
;                 for (int e = 0; e < 8; ++e) xv[j][e] += gt[e] * (hv[j][e] * r1); }
;         }
;         if (x_dst) {
; #pragma unroll
;             for (int j = 0; j < 4; ++j) { if (XDST_BF) *(vu4*)((bf16_t*)x_dst + (size_t)row * DM + 8 * lane + 512 * j) = pack8(xv[j]); else store8f(x_dst + (size_t)row * DM + 8 * lane + 512 * j, xv[j]); }
;         }
;         if (h || ug) {
;             float ss = 0.f;
; #pragma unroll
;             for (int j = 0; j < 4; ++j)
; #pragma unroll
;                 for (int e = 0; e < 8; ++e) ss += xv[j][e] * xv[j][e];
;             ss = wave_sum(ss);
;             const float r2 = rsqrtf(ss * (1.0f / DM) + EPSN);
; #pragma unroll
;             for (int j = 0; j < 4; ++j) { float sh[8], sc[8], o[8]; load8f(mpre + (size_t)b * 12288 + 8 * lane + 512 * j, sh); load8f(mpre + (size_t)b * 12288 + 2048 + 8 * lane + 512 * j, sc);
	v_pk_mul_f32 v[46:47], v[152:153], v[152:153]
	v_add_f32_e32 v36, v157, v36
	v_add_f32_e32 v36, v46, v36
	v_pk_mul_f32 v[150:151], v[148:149], v[148:149]
	v_add_f32_e32 v36, v47, v36
	v_lshlrev_b32_e32 v146, 16, v48
	v_and_b32_e32 v147, 0xffff0000, v48
	v_add_f32_e32 v36, v150, v36
	v_lshlrev_b32_e32 v142, 16, v49
	v_and_b32_e32 v143, 0xffff0000, v49
	v_pk_mul_f32 v[48:49], v[146:147], v[146:147]
	v_add_f32_e32 v36, v151, v36
	v_add_f32_e32 v36, v48, v36
	v_pk_mul_f32 v[144:145], v[142:143], v[142:143]
	v_add_f32_e32 v36, v49, v36
	v_lshlrev_b32_e32 v140, 16, v50
	v_and_b32_e32 v141, 0xffff0000, v50
	v_add_f32_e32 v36, v144, v36
	v_lshlrev_b32_e32 v136, 16, v51
	v_and_b32_e32 v137, 0xffff0000, v51
	v_pk_mul_f32 v[50:51], v[140:141], v[140:141]
	v_add_f32_e32 v36, v145, v36
	v_add_f32_e32 v36, v50, v36
	v_pk_mul_f32 v[138:139], v[136:137], v[136:137]
	v_add_f32_e32 v36, v51, v36
	v_lshlrev_b32_e32 v134, 16, v52
	v_and_b32_e32 v135, 0xffff0000, v52
	v_add_f32_e32 v36, v138, v36
	v_lshlrev_b32_e32 v132, 16, v53
	v_and_b32_e32 v133, 0xffff0000, v53
	v_pk_mul_f32 v[52:53], v[134:135], v[134:135]
	v_add_f32_e32 v36, v139, v36
	v_add_f32_e32 v36, v52, v36
	v_pk_mul_f32 v[34:35], v[132:133], v[132:133]
	v_add_f32_e32 v36, v53, v36
	v_add_f32_e32 v34, v34, v36
	v_add_f32_e32 v34, v35, v34
	v_mov_b32_e32 v35, 0
	v_lshlrev_b32_e32 v130, 16, v37
	v_add_f32_dpp v34, v34, v34 row_shr:1 row_mask:0xf bank_mask:0xf bound_ctrl:1
	v_and_b32_e32 v131, 0xffff0000, v37
	s_mul_hi_u32 s39, s17, 0xc000
	v_add_f32_dpp v34, v34, v34 row_shr:2 row_mask:0xf bank_mask:0xf bound_ctrl:1
	s_mul_i32 s17, s17, 0xc000
	s_nop 0
	v_add_f32_dpp v34, v34, v34 row_shr:4 row_mask:0xf bank_mask:0xf bound_ctrl:1
	s_nop 1
	v_add_f32_dpp v34, v34, v34 row_shr:8 row_mask:0xf bank_mask:0xf bound_ctrl:1
	s_nop 1
	v_mov_b32_dpp v35, v34 row_bcast:15 row_mask:0xa bank_mask:0xf
	v_add_f32_e32 v34, v34, v35
	v_mov_b32_e32 v35, 0
	s_nop 1
	v_mov_b32_dpp v35, v34 row_bcast:31 row_mask:0xc bank_mask:0xf
	v_add_f32_e32 v34, v34, v35
	s_nop 0
	v_readlane_b32 s26, v34, 63
	s_nop 1
	v_fma_f32 v34, s26, v87, v84
	v_mul_f32_e32 v35, 0x4b800000, v34
	v_cmp_gt_f32_e32 vcc, s36, v34
	s_lshl_b64 s[26:27], s[2:3], 12
	s_nop 0
	v_cndmask_b32_e32 v34, v34, v35, vcc
	v_rsq_f32_e32 v34, v34
	s_nop 0
	v_mul_f32_e32 v35, 0x45800000, v34
	v_cndmask_b32_e32 v50, v34, v35, vcc
	v_pk_mul_f32 v[34:35], v[50:51], v[176:177] op_sel_hi:[0,1]
	s_waitcnt vmcnt(6)
	v_pk_fma_f32 v[100:101], v[58:59], v[34:35], v[100:101]
	v_pk_mul_f32 v[34:35], v[50:51], v[172:173] op_sel_hi:[0,1]
	v_pk_fma_f32 v[102:103], v[60:61], v[34:35], v[102:103]
	v_pk_mul_f32 v[34:35], v[50:51], v[170:171] op_sel_hi:[0,1]
	v_pk_fma_f32 v[104:105], v[54:55], v[34:35], v[104:105]
	v_pk_mul_f32 v[34:35], v[50:51], v[166:167] op_sel_hi:[0,1]
	v_pk_fma_f32 v[106:107], v[56:57], v[34:35], v[106:107]
	v_pk_mul_f32 v[34:35], v[50:51], v[164:165] op_sel_hi:[0,1]
	s_waitcnt vmcnt(4)
	v_pk_fma_f32 v[44:45], v[76:77], v[34:35], v[108:109]
	v_pk_mul_f32 v[34:35], v[50:51], v[160:161] op_sel_hi:[0,1]
	v_pk_fma_f32 v[48:49], v[78:79], v[34:35], v[110:111]
	v_pk_mul_f32 v[34:35], v[50:51], v[158:159] op_sel_hi:[0,1]
	v_pk_fma_f32 v[42:43], v[62:63], v[34:35], v[112:113]
	v_pk_mul_f32 v[34:35], v[50:51], v[154:155] op_sel_hi:[0,1]
	v_pk_fma_f32 v[46:47], v[64:65], v[34:35], v[114:115]
	v_pk_mul_f32 v[34:35], v[50:51], v[152:153] op_sel_hi:[0,1]
	v_pk_mul_f32 v[52:53], v[50:51], v[140:141] op_sel_hi:[0,1]
	s_waitcnt vmcnt(3)
	v_pk_fma_f32 v[36:37], v[80:81], v[34:35], v[116:117]
	v_pk_mul_f32 v[34:35], v[50:51], v[148:149] op_sel_hi:[0,1]
	s_waitcnt vmcnt(1)
	v_pk_fma_f32 v[76:77], v[92:93], v[52:53], v[124:125]
	v_pk_mul_f32 v[52:53], v[50:51], v[136:137] op_sel_hi:[0,1]
	v_pk_fma_f32 v[40:41], v[82:83], v[34:35], v[118:119]
	v_pk_mul_f32 v[34:35], v[50:51], v[146:147] op_sel_hi:[0,1]
	v_pk_mul_f32 v[38:39], v[50:51], v[142:143] op_sel_hi:[0,1]
	v_pk_fma_f32 v[78:79], v[94:95], v[52:53], v[126:127]
	v_pk_mul_f32 v[52:53], v[50:51], v[134:135] op_sel_hi:[0,1]
	v_pk_mul_f32 v[50:51], v[50:51], v[132:133] op_sel_hi:[0,1]
	s_waitcnt vmcnt(0)
	v_pk_fma_f32 v[80:81], v[52:53], v[96:97], v[128:129]
	v_pk_fma_f32 v[82:83], v[50:51], v[98:99], v[130:131]
	v_lshl_add_u64 v[54:55], v[68:69], 0, s[26:27]
	v_cvt_pk_bf16_f32 v50, v100, v101
	v_cvt_pk_bf16_f32 v51, v102, v103
	v_cvt_pk_bf16_f32 v52, v104, v105
	v_cvt_pk_bf16_f32 v53, v106, v107
	v_pk_fma_f32 v[34:35], v[88:89], v[34:35], v[120:121]
	v_pk_fma_f32 v[38:39], v[90:91], v[38:39], v[122:123]
	global_store_dwordx4 v[54:55], v[50:53], off
	s_add_u32 s26, s33, s17
	s_addc_u32 s27, s34, s39
	v_cvt_pk_bf16_f32 v50, v44, v45
	v_cvt_pk_bf16_f32 v51, v48, v49
	v_cvt_pk_bf16_f32 v52, v42, v43
	v_cvt_pk_bf16_f32 v53, v46, v47
	global_store_dwordx4 v[54:55], v[50:53], off offset:1024
	v_lshl_add_u64 v[108:109], s[26:27], 0, v[66:67]
	v_add_co_u32_e32 v96, vcc, s38, v108
	v_cvt_pk_bf16_f32 v50, v36, v37
	v_cvt_pk_bf16_f32 v51, v40, v41
	v_cvt_pk_bf16_f32 v52, v34, v35
	v_cvt_pk_bf16_f32 v53, v38, v39
	global_store_dwordx4 v[54:55], v[50:53], off offset:2048
	v_addc_co_u32_e32 v97, vcc, 0, v109, vcc
	s_nop 0
	v_cvt_pk_bf16_f32 v50, v76, v77
	v_cvt_pk_bf16_f32 v51, v78, v79
	v_cvt_pk_bf16_f32 v52, v80, v81
	v_cvt_pk_bf16_f32 v53, v82, v83
	global_store_dwordx4 v[54:55], v[50:53], off offset:3072
	global_load_dwordx4 v[50:53], v66, s[26:27]
	s_nop 0
	global_load_dwordx4 v[54:57], v[96:97], off offset:-4096
	global_load_dwordx4 v[58:61], v66, s[26:27] offset:16
	v_lshl_add_u64 v[88:89], v[108:109], 0, s[8:9]
	global_load_dwordx4 v[62:65], v[88:89], off offset:16
	v_pk_mul_f32 v[90:91], v[100:101], v[100:101]
; __device__ __forceinline__ vu4 pack8(const float (&f)[8]) { vu4 w; w.x = pg8::cvt_pk_bf16(f[0], f[1]); w.y = pg8::cvt_pk_bf16(f[2], f[3]); w.z = pg8::cvt_pk_bf16(f[4], f[5]); w.w = pg8::cvt_pk_bf16(f[6], f[7]); return w; }
; __device__ __forceinline__ float wave_sum(float v) { return lane63(wave_scan_incl(v)); }
; template <bool XSRC_BF, bool XDST_BF> ...
;     ...
;         if (h || ug) {
;             float ss = 0.f;
; #pragma unroll
;             for (int j = 0; j < 4; ++j)
; #pragma unroll
;                 for (int e = 0; e < 8; ++e) ss += xv[j][e] * xv[j][e];
;             ss = wave_sum(ss);
;             const float r2 = rsqrtf(ss * (1.0f / DM) + EPSN);
; #pragma unroll
;             for (int j = 0; j < 4; ++j) { float sh[8], sc[8], o[8]; load8f(mpre + (size_t)b * 12288 + 8 * lane + 512 * j, sh); load8f(mpre + (size_t)b * 12288 + 2048 + 8 * lane + 512 * j, sc);
; #pragma unroll
;                 for (int e = 0; e < 8; ++e) o[e] = xv[j][e] * r2 * sc[e] + sh[e];
;                 if (ug) { const int col = 8 * lane + 512 * j; *(vu4*)(ug + ((size_t)((col >> 4) * 1280 + (row >> 5))) * 768 + (row & 31) * 16 + (col & 8)) = pack8(o); }
;                 else *(vu4*)(h + (size_t)row * DM + 8 * lane + 512 * j) = pack8(o); }
	v_pk_mul_f32 v[92:93], v[102:103], v[102:103]
	v_add_f32_e32 v90, v90, v91
	v_add_f32_e32 v90, v92, v90
	v_pk_mul_f32 v[94:95], v[104:105], v[104:105]
	v_add_f32_e32 v90, v93, v90
	v_add_f32_e32 v90, v94, v90
	v_pk_mul_f32 v[98:99], v[106:107], v[106:107]
	v_add_f32_e32 v90, v95, v90
	v_add_f32_e32 v90, v98, v90
	v_pk_mul_f32 v[110:111], v[44:45], v[44:45]
	v_add_f32_e32 v90, v99, v90
	v_add_f32_e32 v90, v110, v90
	v_pk_mul_f32 v[112:113], v[48:49], v[48:49]
	v_add_f32_e32 v90, v111, v90
	v_add_f32_e32 v90, v112, v90
	v_pk_mul_f32 v[114:115], v[42:43], v[42:43]
	v_add_f32_e32 v90, v113, v90
	v_add_f32_e32 v90, v114, v90
	v_pk_mul_f32 v[116:117], v[46:47], v[46:47]
	v_add_f32_e32 v90, v115, v90
	v_add_f32_e32 v90, v116, v90
	v_pk_mul_f32 v[118:119], v[36:37], v[36:37]
	v_add_f32_e32 v90, v117, v90
	v_add_f32_e32 v90, v118, v90
	v_pk_mul_f32 v[120:121], v[40:41], v[40:41]
	v_add_f32_e32 v90, v119, v90
	v_add_f32_e32 v90, v120, v90
	v_pk_mul_f32 v[122:123], v[34:35], v[34:35]
	v_add_f32_e32 v90, v121, v90
	v_add_f32_e32 v90, v122, v90
	v_pk_mul_f32 v[124:125], v[38:39], v[38:39]
	v_add_f32_e32 v90, v123, v90
	v_add_f32_e32 v90, v124, v90
	v_pk_mul_f32 v[126:127], v[76:77], v[76:77]
	v_add_f32_e32 v90, v125, v90
	v_add_f32_e32 v90, v126, v90
	v_pk_mul_f32 v[128:129], v[78:79], v[78:79]
	v_add_f32_e32 v90, v127, v90
	v_add_f32_e32 v90, v128, v90
	v_pk_mul_f32 v[130:131], v[80:81], v[80:81]
	v_add_f32_e32 v90, v129, v90
	v_add_f32_e32 v90, v130, v90
	v_pk_mul_f32 v[132:133], v[82:83], v[82:83]
	v_add_f32_e32 v90, v131, v90
	v_add_f32_e32 v90, v132, v90
	v_add_f32_e32 v90, v133, v90
	v_mov_b32_e32 v91, 0
	s_and_b64 s[14:15], s[14:15], s[24:25]
	v_add_f32_dpp v90, v90, v90 row_shr:1 row_mask:0xf bank_mask:0xf bound_ctrl:1
	s_add_i32 s30, s30, 1
	s_nop 0
	v_add_f32_dpp v90, v90, v90 row_shr:2 row_mask:0xf bank_mask:0xf bound_ctrl:1
	s_nop 1
	v_add_f32_dpp v90, v90, v90 row_shr:4 row_mask:0xf bank_mask:0xf bound_ctrl:1
	s_nop 1
	v_add_f32_dpp v90, v90, v90 row_shr:8 row_mask:0xf bank_mask:0xf bound_ctrl:1
	s_nop 1
	v_mov_b32_dpp v91, v90 row_bcast:15 row_mask:0xa bank_mask:0xf
	v_add_f32_e32 v90, v90, v91
	v_mov_b32_e32 v91, 0
	s_nop 1
	v_mov_b32_dpp v91, v90 row_bcast:31 row_mask:0xc bank_mask:0xf
	v_add_f32_e32 v90, v90, v91
	s_nop 0
	v_readlane_b32 s17, v90, 63
	s_nop 1
	v_fma_f32 v90, s17, v87, v84
	v_mul_f32_e32 v91, 0x4b800000, v90
	v_cmp_gt_f32_e32 vcc, s36, v90
	s_lshr_b32 s17, s2, 5
	s_lshl_b32 s2, s2, 5
	v_cndmask_b32_e32 v90, v90, v91, vcc
	v_rsq_f32_e32 v90, v90
	s_and_b32 s2, s2, 0x3e0
	s_and_b32 s98, s2, 0x60
	v_add_u32_e32 v214, s98, v210
	v_lshl_add_u64 v[112:113], v[74:75], 0, s[2:3]
	s_mov_b32 s2, s16
	v_mul_f32_e32 v91, 0x45800000, v90
	v_cndmask_b32_e32 v110, v90, v91, vcc
	v_pk_mul_f32 v[90:91], v[100:101], v[110:111] op_sel_hi:[1,0]
	v_pk_mul_f32 v[44:45], v[44:45], v[110:111] op_sel_hi:[1,0]
	s_waitcnt vmcnt(2)
	v_pk_fma_f32 v[50:51], v[54:55], v[90:91], v[50:51]
	v_pk_mul_f32 v[54:55], v[102:103], v[110:111] op_sel_hi:[1,0]
	v_cvt_pk_bf16_f32 v50, v50, v51
	v_pk_fma_f32 v[52:53], v[56:57], v[54:55], v[52:53]
	v_pk_mul_f32 v[54:55], v[104:105], v[110:111] op_sel_hi:[1,0]
	v_pk_mul_f32 v[56:57], v[106:107], v[110:111] op_sel_hi:[1,0]
	s_waitcnt vmcnt(0)
	v_pk_fma_f32 v[54:55], v[62:63], v[54:55], v[58:59]
	v_pk_fma_f32 v[56:57], v[64:65], v[56:57], v[60:61]
	v_add_u32_e32 v104, s17, v1
	v_cvt_pk_bf16_f32 v51, v52, v53
	v_cvt_pk_bf16_f32 v52, v54, v55
	v_cvt_pk_bf16_f32 v53, v56, v57
	v_mad_u64_u32 v[54:55], s[40:41], v104, s37, v[112:113]
	ds_write_b128 v214, v[50:53]
	global_load_dwordx4 v[50:53], v[88:89], off offset:2048
	s_nop 0
	global_load_dwordx4 v[54:57], v66, s[26:27] offset:2048
	global_load_dwordx4 v[58:61], v66, s[26:27] offset:2064
	global_load_dwordx4 v[62:65], v[88:89], off offset:2064
	v_pk_mul_f32 v[42:43], v[42:43], v[110:111] op_sel_hi:[1,0]
	v_pk_mul_f32 v[48:49], v[48:49], v[110:111] op_sel_hi:[1,0]
	v_pk_mul_f32 v[36:37], v[36:37], v[110:111] op_sel_hi:[1,0]
	v_pk_mul_f32 v[34:35], v[34:35], v[110:111] op_sel_hi:[1,0]
	v_pk_mul_f32 v[40:41], v[40:41], v[110:111] op_sel_hi:[1,0]
	s_waitcnt vmcnt(2)
	v_pk_fma_f32 v[44:45], v[44:45], v[50:51], v[54:55]
	v_pk_fma_f32 v[48:49], v[48:49], v[52:53], v[56:57]
	s_waitcnt vmcnt(0)
	v_pk_fma_f32 v[50:51], v[42:43], v[62:63], v[58:59]
	v_pk_mul_f32 v[42:43], v[46:47], v[110:111] op_sel_hi:[1,0]
	v_add_co_u32_e32 v58, vcc, s35, v108
	v_pk_fma_f32 v[46:47], v[42:43], v[64:65], v[60:61]
	v_cvt_pk_bf16_f32 v42, v44, v45
	v_cvt_pk_bf16_f32 v45, v46, v47
	v_add_u32_e32 v46, 0xa000, v104
	v_cvt_pk_bf16_f32 v43, v48, v49
	v_cvt_pk_bf16_f32 v44, v50, v51
	v_mad_u64_u32 v[46:47], s[26:27], v46, s37, v[112:113]
	ds_write_b128 v214, v[42:45] offset:4608
	v_addc_co_u32_e32 v59, vcc, 0, v109, vcc
	v_lshl_add_u64 v[50:51], v[108:109], 0, s[4:5]
	v_lshl_add_u64 v[54:55], v[108:109], 0, s[10:11]
	global_load_dwordx4 v[42:45], v[58:59], off
	global_load_dwordx4 v[46:49], v[96:97], off
	v_mov_b64_e32 v[64:65], v[4:5]
	global_load_dwordx4 v[50:53], v[50:51], off offset:16
	v_mov_b64_e32 v[62:63], v[2:3]
	global_load_dwordx4 v[54:57], v[54:55], off offset:16
	v_add_u32_e32 v2, 0x1e000, v104
	s_and_b64 vcc, exec, s[14:15]
	v_pk_mul_f32 v[4:5], v[78:79], v[110:111] op_sel_hi:[1,0]
	s_waitcnt vmcnt(2)
; __device__ __forceinline__ vu4 pack8(const float (&f)[8]) { vu4 w; w.x = pg8::cvt_pk_bf16(f[0], f[1]); w.y = pg8::cvt_pk_bf16(f[2], f[3]); w.z = pg8::cvt_pk_bf16(f[4], f[5]); w.w = pg8::cvt_pk_bf16(f[6], f[7]); return w; }
; template <bool XSRC_BF, bool XDST_BF> ...
;     ...
; #pragma unroll
;             for (int j = 0; j < 4; ++j) { float sh[8], sc[8], o[8]; load8f(mpre + (size_t)b * 12288 + 8 * lane + 512 * j, sh); load8f(mpre + (size_t)b * 12288 + 2048 + 8 * lane + 512 * j, sc);
; #pragma unroll
;                 for (int e = 0; e < 8; ++e) o[e] = xv[j][e] * r2 * sc[e] + sh[e];
;                 if (ug) { const int col = 8 * lane + 512 * j; *(vu4*)(ug + ((size_t)((col >> 4) * 1280 + (row >> 5))) * 768 + (row & 31) * 16 + (col & 8)) = pack8(o); }
;                 else *(vu4*)(h + (size_t)row * DM + 8 * lane + 512 * j) = pack8(o); }
	v_pk_fma_f32 v[36:37], v[36:37], v[46:47], v[42:43]
	v_pk_fma_f32 v[40:41], v[40:41], v[48:49], v[44:45]
	v_mov_b64_e32 v[48:49], v[28:29]
	v_mov_b64_e32 v[46:47], v[26:27]
	s_waitcnt vmcnt(0)
	v_pk_fma_f32 v[42:43], v[34:35], v[54:55], v[50:51]
	v_pk_mul_f32 v[34:35], v[38:39], v[110:111] op_sel_hi:[1,0]
	s_nop 0
	v_pk_fma_f32 v[38:39], v[34:35], v[56:57], v[52:53]
	v_cvt_pk_bf16_f32 v34, v36, v37
	v_cvt_pk_bf16_f32 v37, v38, v39
	v_add_u32_e32 v38, 0x14000, v104
	v_cvt_pk_bf16_f32 v35, v40, v41
	v_cvt_pk_bf16_f32 v36, v42, v43
	v_mad_u64_u32 v[38:39], s[26:27], v38, s37, v[112:113]
	ds_write_b128 v214, v[34:37] offset:9216
	v_mov_b64_e32 v[40:41], v[12:13]
	v_mov_b64_e32 v[38:39], v[10:11]
	v_lshl_add_u64 v[34:35], v[108:109], 0, s[6:7]
	global_load_dwordx4 v[88:91], v[58:59], off offset:2048
	global_load_dwordx4 v[92:95], v[34:35], off offset:16
	s_nop 0
	global_load_dwordx4 v[96:99], v[96:97], off offset:2048
	v_lshl_add_u64 v[34:35], v[108:109], 0, s[12:13]
	global_load_dwordx4 v[100:103], v[34:35], off offset:16
	v_mov_b64_e32 v[60:61], v[8:9]
	v_mov_b64_e32 v[58:59], v[6:7]
	v_mad_u64_u32 v[6:7], s[14:15], v2, s37, v[112:113]
	v_pk_mul_f32 v[2:3], v[76:77], v[110:111] op_sel_hi:[1,0]
	v_pk_mul_f32 v[8:9], v[80:81], v[110:111] op_sel_hi:[1,0]
	v_pk_mul_f32 v[10:11], v[82:83], v[110:111] op_sel_hi:[1,0]
	v_mov_b64_e32 v[44:45], v[16:17]
	v_mov_b64_e32 v[52:53], v[32:33]
	v_mov_b64_e32 v[56:57], v[20:21]
	v_mov_b64_e32 v[36:37], v[24:25]
	v_mov_b64_e32 v[42:43], v[14:15]
	v_mov_b64_e32 v[50:51], v[30:31]
	v_mov_b64_e32 v[54:55], v[18:19]
	v_mov_b64_e32 v[34:35], v[22:23]
	s_waitcnt vmcnt(1)
	v_pk_fma_f32 v[2:3], v[2:3], v[96:97], v[88:89]
	v_pk_fma_f32 v[4:5], v[4:5], v[98:99], v[90:91]
	s_waitcnt vmcnt(0)
	v_pk_fma_f32 v[8:9], v[8:9], v[100:101], v[92:93]
	v_pk_fma_f32 v[10:11], v[10:11], v[102:103], v[94:95]
	v_cvt_pk_bf16_f32 v2, v2, v3
	v_cvt_pk_bf16_f32 v3, v4, v5
	v_cvt_pk_bf16_f32 v4, v8, v9
	v_cvt_pk_bf16_f32 v5, v10, v11
	ds_write_b128 v214, v[2:5] offset:13824
	s_cmp_lg_u32 s98, 0x60
	s_cbranch_scc1 .Lp10_noflush
	s_mul_i32 s98, s17, 0x600
	s_mov_b32 s99, 0
	v_lshl_add_u64 v[216:217], s[98:99], 0, v[212:213]
	s_waitcnt lgkmcnt(0)
	ds_read_b128 v[218:221], v211
	ds_read_b128 v[222:225], v211 offset:1152
	ds_read_b128 v[226:229], v211 offset:2304
	ds_read_b128 v[230:233], v211 offset:3456
	s_waitcnt lgkmcnt(3)
	global_store_dwordx4 v[216:217], v[218:221], off
	v_lshl_add_u64 v[216:217], s[100:101], 0, v[216:217]
	s_waitcnt lgkmcnt(2)
	global_store_dwordx4 v[216:217], v[222:225], off
	v_lshl_add_u64 v[216:217], s[100:101], 0, v[216:217]
	s_waitcnt lgkmcnt(1)
	global_store_dwordx4 v[216:217], v[226:229], off
	v_lshl_add_u64 v[216:217], s[100:101], 0, v[216:217]
	s_waitcnt lgkmcnt(0)
	global_store_dwordx4 v[216:217], v[230:233], off
	v_lshl_add_u64 v[216:217], s[100:101], 0, v[216:217]
	ds_read_b128 v[218:221], v211 offset:4608
	ds_read_b128 v[222:225], v211 offset:5760
	ds_read_b128 v[226:229], v211 offset:6912
	ds_read_b128 v[230:233], v211 offset:8064
	s_waitcnt lgkmcnt(3)
	global_store_dwordx4 v[216:217], v[218:221], off
	v_lshl_add_u64 v[216:217], s[100:101], 0, v[216:217]
	s_waitcnt lgkmcnt(2)
	global_store_dwordx4 v[216:217], v[222:225], off
	v_lshl_add_u64 v[216:217], s[100:101], 0, v[216:217]
	s_waitcnt lgkmcnt(1)
	global_store_dwordx4 v[216:217], v[226:229], off
	v_lshl_add_u64 v[216:217], s[100:101], 0, v[216:217]
	s_waitcnt lgkmcnt(0)
	global_store_dwordx4 v[216:217], v[230:233], off
	v_lshl_add_u64 v[216:217], s[100:101], 0, v[216:217]
	ds_read_b128 v[218:221], v211 offset:9216
	ds_read_b128 v[222:225], v211 offset:10368
	ds_read_b128 v[226:229], v211 offset:11520
	ds_read_b128 v[230:233], v211 offset:12672
	s_waitcnt lgkmcnt(3)
	global_store_dwordx4 v[216:217], v[218:221], off
	v_lshl_add_u64 v[216:217], s[100:101], 0, v[216:217]
	s_waitcnt lgkmcnt(2)
	global_store_dwordx4 v[216:217], v[222:225], off
	v_lshl_add_u64 v[216:217], s[100:101], 0, v[216:217]
	s_waitcnt lgkmcnt(1)
	global_store_dwordx4 v[216:217], v[226:229], off
	v_lshl_add_u64 v[216:217], s[100:101], 0, v[216:217]
	s_waitcnt lgkmcnt(0)
	global_store_dwordx4 v[216:217], v[230:233], off
	v_lshl_add_u64 v[216:217], s[100:101], 0, v[216:217]
	ds_read_b128 v[218:221], v211 offset:13824
	ds_read_b128 v[222:225], v211 offset:14976
	ds_read_b128 v[226:229], v211 offset:16128
	ds_read_b128 v[230:233], v211 offset:17280
	s_waitcnt lgkmcnt(3)
	global_store_dwordx4 v[216:217], v[218:221], off
	v_lshl_add_u64 v[216:217], s[100:101], 0, v[216:217]
	s_waitcnt lgkmcnt(2)
	global_store_dwordx4 v[216:217], v[222:225], off
	v_lshl_add_u64 v[216:217], s[100:101], 0, v[216:217]
	s_waitcnt lgkmcnt(1)
	global_store_dwordx4 v[216:217], v[226:229], off
	v_lshl_add_u64 v[216:217], s[100:101], 0, v[216:217]
	s_waitcnt lgkmcnt(0)
	global_store_dwordx4 v[216:217], v[230:233], off
.Lp10_noflush:
	s_cbranch_vccz .LBB0_1101
